# stack4: stack2 + P0 x->X loop with all 8 row loads hoisted (was load-wait-store serialized) + p-loop input pointers hoisted to scalar loads
# speedup vs baseline: 1.0002x; 1.0002x over previous
; #define GAS __attribute__((address_space(1)))
; __device__ __forceinline__ unsigned f2bf(float f) { unsigned u = __builtin_bit_cast(unsigned, f); return (u + 0x7fffu + ((u >> 16) & 1u)) >> 16; }
; __device__ __forceinline__ unsigned pk2(float lo, float hi) { return f2bf(lo) | (f2bf(hi) << 16); }
; __global__ void __launch_bounds__(NWAVES * 64, 2) trunk_fwd(Args args) {
;     ...
;             for (int m = gw; m < M; m += NGW) {
;                 const float* xrow = m < MP ? ka->in[0] + (size_t)m * DM : ka->in[1] + (size_t)(m - MP) * DM;
;                 const GAS f32x4* xr = (const GAS f32x4*)xrow + lane; GAS v2u* xo = (GAS v2u*)(X + (size_t)m * DM) + lane; f32x4 v[8]; float s = 0.f;
; #pragma unroll
;                 for (int j = 0; j < 8; ++j) { v[j] = xr[64 * j]; v2u w_; w_.x = pk2(v[j].x, v[j].y); w_.y = pk2(v[j].z, v[j].w); xo[64 * j] = w_; s += (v[j].x * v[j].x + v[j].y * v[j].y) + (v[j].z * v[j].z + v[j].w * v[j].w); }
;                 s = wave_sum(s); if (lane < 8) SS(0)[(size_t)m * 8 + lane] = lane == 0 ? (bf16)f2bf(s) : (bf16)0;
.LBB0_76:
	s_lshl_b64 s[24:25], s[20:21], 12
	global_load_dwordx4 v[12:15], v2, s[22:23]
	global_load_dwordx4 v[16:19], v2, s[22:23] offset:1024
	global_load_dwordx4 v[20:23], v2, s[22:23] offset:2048
	global_load_dwordx4 v[24:27], v2, s[22:23] offset:3072
	v_lshl_add_u64 v[44:45], s[22:23], 0, v[2:3]
	v_lshl_add_u64 v[8:9], v[4:5], 0, s[24:25]
	v_add_co_u32_e32 v44, vcc, s27, v44
	s_nop 1
	v_addc_co_u32_e32 v45, vcc, 0, v45, vcc
	global_load_dwordx4 v[28:31], v[44:45], off
	global_load_dwordx4 v[32:35], v[44:45], off offset:1024
	global_load_dwordx4 v[36:39], v[44:45], off offset:2048
	global_load_dwordx4 v[40:43], v[44:45], off offset:3072
	s_waitcnt vmcnt(7)
	v_and_b32_sdwa v47, v15, v10 dst_sel:DWORD dst_unused:UNUSED_PAD src0_sel:WORD_1 src1_sel:DWORD
	v_and_b32_sdwa v48, v13, v10 dst_sel:DWORD dst_unused:UNUSED_PAD src0_sel:WORD_1 src1_sel:DWORD
	v_and_b32_sdwa v49, v14, v10 dst_sel:DWORD dst_unused:UNUSED_PAD src0_sel:WORD_1 src1_sel:DWORD
	v_and_b32_sdwa v46, v12, v10 dst_sel:DWORD dst_unused:UNUSED_PAD src0_sel:WORD_1 src1_sel:DWORD
	v_add3_u32 v47, v15, v47, s26
	v_add3_u32 v48, v13, v48, s26
	v_add3_u32 v46, v12, v46, s26
	v_add3_u32 v49, v14, v49, s26
	v_and_b32_e32 v47, 0xffff0000, v47
	v_and_b32_e32 v48, 0xffff0000, v48
	v_or_b32_sdwa v47, v47, v49 dst_sel:DWORD dst_unused:UNUSED_PAD src0_sel:DWORD src1_sel:WORD_1
	v_or_b32_sdwa v46, v48, v46 dst_sel:DWORD dst_unused:UNUSED_PAD src0_sel:DWORD src1_sel:WORD_1
	global_store_dwordx2 v[8:9], v[46:47], off
	s_waitcnt vmcnt(7)
	v_and_b32_sdwa v51, v19, v10 dst_sel:DWORD dst_unused:UNUSED_PAD src0_sel:WORD_1 src1_sel:DWORD
	v_and_b32_sdwa v52, v17, v10 dst_sel:DWORD dst_unused:UNUSED_PAD src0_sel:WORD_1 src1_sel:DWORD
	v_and_b32_sdwa v53, v18, v10 dst_sel:DWORD dst_unused:UNUSED_PAD src0_sel:WORD_1 src1_sel:DWORD
	v_and_b32_sdwa v50, v16, v10 dst_sel:DWORD dst_unused:UNUSED_PAD src0_sel:WORD_1 src1_sel:DWORD
	v_add3_u32 v51, v19, v51, s26
	v_add3_u32 v52, v17, v52, s26
	v_add3_u32 v50, v16, v50, s26
	v_add3_u32 v53, v18, v53, s26
	v_and_b32_e32 v51, 0xffff0000, v51
	v_and_b32_e32 v52, 0xffff0000, v52
	v_or_b32_sdwa v51, v51, v53 dst_sel:DWORD dst_unused:UNUSED_PAD src0_sel:DWORD src1_sel:WORD_1
	v_or_b32_sdwa v50, v52, v50 dst_sel:DWORD dst_unused:UNUSED_PAD src0_sel:DWORD src1_sel:WORD_1
	global_store_dwordx2 v[8:9], v[50:51], off offset:512
	s_waitcnt vmcnt(7)
	v_and_b32_sdwa v47, v23, v10 dst_sel:DWORD dst_unused:UNUSED_PAD src0_sel:WORD_1 src1_sel:DWORD
	v_and_b32_sdwa v48, v21, v10 dst_sel:DWORD dst_unused:UNUSED_PAD src0_sel:WORD_1 src1_sel:DWORD
	v_and_b32_sdwa v49, v22, v10 dst_sel:DWORD dst_unused:UNUSED_PAD src0_sel:WORD_1 src1_sel:DWORD
	v_and_b32_sdwa v46, v20, v10 dst_sel:DWORD dst_unused:UNUSED_PAD src0_sel:WORD_1 src1_sel:DWORD
	v_add3_u32 v47, v23, v47, s26
	v_add3_u32 v48, v21, v48, s26
	v_add3_u32 v46, v20, v46, s26
	v_add3_u32 v49, v22, v49, s26
	v_and_b32_e32 v47, 0xffff0000, v47
	v_and_b32_e32 v48, 0xffff0000, v48
	v_or_b32_sdwa v47, v47, v49 dst_sel:DWORD dst_unused:UNUSED_PAD src0_sel:DWORD src1_sel:WORD_1
	v_or_b32_sdwa v46, v48, v46 dst_sel:DWORD dst_unused:UNUSED_PAD src0_sel:DWORD src1_sel:WORD_1
	global_store_dwordx2 v[8:9], v[46:47], off offset:1024
	s_waitcnt vmcnt(7)
	v_and_b32_sdwa v51, v27, v10 dst_sel:DWORD dst_unused:UNUSED_PAD src0_sel:WORD_1 src1_sel:DWORD
	v_and_b32_sdwa v52, v25, v10 dst_sel:DWORD dst_unused:UNUSED_PAD src0_sel:WORD_1 src1_sel:DWORD
	v_and_b32_sdwa v53, v26, v10 dst_sel:DWORD dst_unused:UNUSED_PAD src0_sel:WORD_1 src1_sel:DWORD
	v_and_b32_sdwa v50, v24, v10 dst_sel:DWORD dst_unused:UNUSED_PAD src0_sel:WORD_1 src1_sel:DWORD
	v_add3_u32 v51, v27, v51, s26
	v_add3_u32 v52, v25, v52, s26
	v_add3_u32 v50, v24, v50, s26
	v_add3_u32 v53, v26, v53, s26
	v_and_b32_e32 v51, 0xffff0000, v51
	v_and_b32_e32 v52, 0xffff0000, v52
	v_or_b32_sdwa v51, v51, v53 dst_sel:DWORD dst_unused:UNUSED_PAD src0_sel:DWORD src1_sel:WORD_1
	v_or_b32_sdwa v50, v52, v50 dst_sel:DWORD dst_unused:UNUSED_PAD src0_sel:DWORD src1_sel:WORD_1
	global_store_dwordx2 v[8:9], v[50:51], off offset:1536
	s_waitcnt vmcnt(7)
	v_and_b32_sdwa v47, v31, v10 dst_sel:DWORD dst_unused:UNUSED_PAD src0_sel:WORD_1 src1_sel:DWORD
	v_and_b32_sdwa v48, v29, v10 dst_sel:DWORD dst_unused:UNUSED_PAD src0_sel:WORD_1 src1_sel:DWORD
	v_and_b32_sdwa v49, v30, v10 dst_sel:DWORD dst_unused:UNUSED_PAD src0_sel:WORD_1 src1_sel:DWORD
	v_and_b32_sdwa v46, v28, v10 dst_sel:DWORD dst_unused:UNUSED_PAD src0_sel:WORD_1 src1_sel:DWORD
	v_add3_u32 v47, v31, v47, s26
	v_add3_u32 v48, v29, v48, s26
	v_add3_u32 v46, v28, v46, s26
	v_add3_u32 v49, v30, v49, s26
	v_and_b32_e32 v47, 0xffff0000, v47
	v_and_b32_e32 v48, 0xffff0000, v48
	v_or_b32_sdwa v47, v47, v49 dst_sel:DWORD dst_unused:UNUSED_PAD src0_sel:DWORD src1_sel:WORD_1
	v_or_b32_sdwa v46, v48, v46 dst_sel:DWORD dst_unused:UNUSED_PAD src0_sel:DWORD src1_sel:WORD_1
	global_store_dwordx2 v[8:9], v[46:47], off offset:2048
	s_waitcnt vmcnt(7)
	v_and_b32_sdwa v51, v35, v10 dst_sel:DWORD dst_unused:UNUSED_PAD src0_sel:WORD_1 src1_sel:DWORD
	v_and_b32_sdwa v52, v33, v10 dst_sel:DWORD dst_unused:UNUSED_PAD src0_sel:WORD_1 src1_sel:DWORD
	v_and_b32_sdwa v53, v34, v10 dst_sel:DWORD dst_unused:UNUSED_PAD src0_sel:WORD_1 src1_sel:DWORD
	v_and_b32_sdwa v50, v32, v10 dst_sel:DWORD dst_unused:UNUSED_PAD src0_sel:WORD_1 src1_sel:DWORD
	v_add3_u32 v51, v35, v51, s26
	v_add3_u32 v52, v33, v52, s26
	v_add3_u32 v50, v32, v50, s26
	v_add3_u32 v53, v34, v53, s26
	v_and_b32_e32 v51, 0xffff0000, v51
	v_and_b32_e32 v52, 0xffff0000, v52
	v_or_b32_sdwa v51, v51, v53 dst_sel:DWORD dst_unused:UNUSED_PAD src0_sel:DWORD src1_sel:WORD_1
	v_or_b32_sdwa v50, v52, v50 dst_sel:DWORD dst_unused:UNUSED_PAD src0_sel:DWORD src1_sel:WORD_1
	global_store_dwordx2 v[8:9], v[50:51], off offset:2560
	s_waitcnt vmcnt(7)
; #define GAS __attribute__((address_space(1)))
; __device__ __forceinline__ unsigned f2bf(float f) { unsigned u = __builtin_bit_cast(unsigned, f); return (u + 0x7fffu + ((u >> 16) & 1u)) >> 16; }
; __device__ __forceinline__ unsigned pk2(float lo, float hi) { return f2bf(lo) | (f2bf(hi) << 16); }
; __global__ void __launch_bounds__(NWAVES * 64, 2) trunk_fwd(Args args) {
;     ...
;                 const GAS f32x4* xr = (const GAS f32x4*)xrow + lane; GAS v2u* xo = (GAS v2u*)(X + (size_t)m * DM) + lane; f32x4 v[8]; float s = 0.f;
; #pragma unroll
;                 for (int j = 0; j < 8; ++j) { v[j] = xr[64 * j]; v2u w_; w_.x = pk2(v[j].x, v[j].y); w_.y = pk2(v[j].z, v[j].w); xo[64 * j] = w_; s += (v[j].x * v[j].x + v[j].y * v[j].y) + (v[j].z * v[j].z + v[j].w * v[j].w); }
;                 s = wave_sum(s); if (lane < 8) SS(0)[(size_t)m * 8 + lane] = lane == 0 ? (bf16)f2bf(s) : (bf16)0;
;     ...
;             constexpr int CHL = M * DPLE / 8;
;             for (int c = vcu * (NWAVES * 64) + tid; c < DEPTH * CHL; c += G * NWAVES * 64) {
;                 const int L = c / CHL, cc = c % CHL, row = cc >> 5, col = (cc & 31) * 8;
;                 const float* src = row < MP ? ka->in[2] + ((size_t)L * MP + row) * DPLE + col : ka->in[3] + ((size_t)L * MS + (row - MP)) * DPLE + col;
;                 const f32x4 a = ((const GAS f32x4*)src)[0], b = ((const GAS f32x4*)src)[1]; v4u o; o.x = pk2(a.x, a.y); o.y = pk2(a.z, a.w); o.z = pk2(b.x, b.y); o.w = pk2(b.z, b.w);
;                 *(GAS v4u*)(APLE + (size_t)row * KPLE + col) = o;
	v_and_b32_sdwa v47, v39, v10 dst_sel:DWORD dst_unused:UNUSED_PAD src0_sel:WORD_1 src1_sel:DWORD
	v_and_b32_sdwa v48, v37, v10 dst_sel:DWORD dst_unused:UNUSED_PAD src0_sel:WORD_1 src1_sel:DWORD
	v_and_b32_sdwa v49, v38, v10 dst_sel:DWORD dst_unused:UNUSED_PAD src0_sel:WORD_1 src1_sel:DWORD
	v_and_b32_sdwa v46, v36, v10 dst_sel:DWORD dst_unused:UNUSED_PAD src0_sel:WORD_1 src1_sel:DWORD
	v_add3_u32 v47, v39, v47, s26
	v_add3_u32 v48, v37, v48, s26
	v_add3_u32 v46, v36, v46, s26
	v_add3_u32 v49, v38, v49, s26
	v_and_b32_e32 v47, 0xffff0000, v47
	v_and_b32_e32 v48, 0xffff0000, v48
	v_or_b32_sdwa v47, v47, v49 dst_sel:DWORD dst_unused:UNUSED_PAD src0_sel:DWORD src1_sel:WORD_1
	v_or_b32_sdwa v46, v48, v46 dst_sel:DWORD dst_unused:UNUSED_PAD src0_sel:DWORD src1_sel:WORD_1
	global_store_dwordx2 v[8:9], v[46:47], off offset:3072
	s_waitcnt vmcnt(7)
	v_and_b32_sdwa v51, v43, v10 dst_sel:DWORD dst_unused:UNUSED_PAD src0_sel:WORD_1 src1_sel:DWORD
	v_and_b32_sdwa v52, v41, v10 dst_sel:DWORD dst_unused:UNUSED_PAD src0_sel:WORD_1 src1_sel:DWORD
	v_and_b32_sdwa v53, v42, v10 dst_sel:DWORD dst_unused:UNUSED_PAD src0_sel:WORD_1 src1_sel:DWORD
	v_and_b32_sdwa v50, v40, v10 dst_sel:DWORD dst_unused:UNUSED_PAD src0_sel:WORD_1 src1_sel:DWORD
	v_add3_u32 v51, v43, v51, s26
	v_add3_u32 v52, v41, v52, s26
	v_add3_u32 v50, v40, v50, s26
	v_add3_u32 v53, v42, v53, s26
	v_and_b32_e32 v51, 0xffff0000, v51
	v_and_b32_e32 v52, 0xffff0000, v52
	v_or_b32_sdwa v51, v51, v53 dst_sel:DWORD dst_unused:UNUSED_PAD src0_sel:DWORD src1_sel:WORD_1
	v_or_b32_sdwa v50, v52, v50 dst_sel:DWORD dst_unused:UNUSED_PAD src0_sel:DWORD src1_sel:WORD_1
	global_store_dwordx2 v[8:9], v[50:51], off offset:3584
	v_mul_f32_e32 v11, v13, v13
	v_mul_f32_e32 v13, v15, v15
	v_fmac_f32_e32 v11, v12, v12
	v_fmac_f32_e32 v13, v14, v14
	v_add_f32_e32 v11, v11, v13
	v_mul_f32_e32 v12, v17, v17
	v_mul_f32_e32 v13, v19, v19
	v_fmac_f32_e32 v12, v16, v16
	v_fmac_f32_e32 v13, v18, v18
	v_add_f32_e32 v12, v12, v13
	v_add_f32_e32 v11, v11, v12
	v_mul_f32_e32 v12, v21, v21
	v_mul_f32_e32 v13, v23, v23
	v_fmac_f32_e32 v12, v20, v20
	v_fmac_f32_e32 v13, v22, v22
	v_add_f32_e32 v12, v12, v13
	v_add_f32_e32 v11, v11, v12
	v_mul_f32_e32 v12, v25, v25
	v_mul_f32_e32 v13, v27, v27
	v_fmac_f32_e32 v12, v24, v24
	v_fmac_f32_e32 v13, v26, v26
	v_add_f32_e32 v12, v12, v13
	v_add_f32_e32 v11, v11, v12
	v_mul_f32_e32 v12, v29, v29
	v_mul_f32_e32 v13, v31, v31
	v_fmac_f32_e32 v12, v28, v28
	v_fmac_f32_e32 v13, v30, v30
	v_add_f32_e32 v12, v12, v13
	v_add_f32_e32 v11, v11, v12
	v_mul_f32_e32 v12, v33, v33
	v_mul_f32_e32 v13, v35, v35
	v_fmac_f32_e32 v12, v32, v32
	v_fmac_f32_e32 v13, v34, v34
	v_add_f32_e32 v12, v12, v13
	v_add_f32_e32 v11, v11, v12
	v_mul_f32_e32 v12, v37, v37
	v_mul_f32_e32 v13, v39, v39
	v_fmac_f32_e32 v12, v36, v36
	v_fmac_f32_e32 v13, v38, v38
	v_add_f32_e32 v12, v12, v13
	v_add_f32_e32 v11, v11, v12
	v_mul_f32_e32 v12, v41, v41
	v_mul_f32_e32 v13, v43, v43
	v_fmac_f32_e32 v12, v40, v40
	v_fmac_f32_e32 v13, v42, v42
	v_add_f32_e32 v12, v12, v13
	v_add_f32_e32 v11, v11, v12
	ds_swizzle_b32 v12, v11 offset:swizzle(SWAP,1)
	s_waitcnt lgkmcnt(0)
	v_add_f32_e32 v11, v11, v12
	ds_swizzle_b32 v12, v11 offset:swizzle(SWAP,2)
	s_waitcnt lgkmcnt(0)
	v_add_f32_e32 v11, v11, v12
	ds_swizzle_b32 v12, v11 offset:swizzle(SWAP,4)
	s_waitcnt lgkmcnt(0)
	v_add_f32_e32 v11, v11, v12
	ds_swizzle_b32 v12, v11 offset:swizzle(SWAP,8)
	s_waitcnt lgkmcnt(0)
	v_add_f32_e32 v11, v11, v12
	ds_swizzle_b32 v17, v11 offset:swizzle(SWAP,16)
	s_waitcnt lgkmcnt(0)
	v_add_f32_e32 v8, v11, v17
	v_mov_b32_e32 v9, v8
	s_nop 1
	v_permlane32_swap_b32_e32 v8, v9
	s_and_saveexec_b64 s[22:23], s[4:5]
	s_cbranch_execz .LBB0_71
	v_add_f32_e32 v8, v8, v9
	v_bfe_u32 v9, v8, 16, 1
	s_mov_b64 vcc, s[6:7]
	v_add3_u32 v8, v8, v9, s26
	v_cndmask_b32_sdwa v11, v3, v8, vcc dst_sel:DWORD dst_unused:UNUSED_PAD src0_sel:DWORD src1_sel:WORD_1
	v_lshl_add_u64 v[8:9], s[20:21], 4, v[6:7]
	global_store_short v[8:9], v11, off
	s_branch .LBB0_71
.LBB0_78:
	v_readlane_b32 s4, v253, 4
	s_nop 1
	v_lshl_add_u32 v1, s4, 9, v1
	s_mov_b32 s4, 0x110000
	v_cmp_gt_i32_e32 vcc, s4, v1
	s_and_saveexec_b64 s[4:5], vcc
	s_cbranch_execz .LBB0_81
	s_load_dword s6, s[0:1], 0xf0
	s_load_dwordx4 s[28:31], s[8:9], 0x10
	s_add_u32 s18, s10, 0x3d300000
	s_addc_u32 s19, s11, 0
	v_lshlrev_b32_e32 v6, 3, v1
	s_mov_b32 s12, 0x78787879
	s_waitcnt lgkmcnt(0)
	v_mov_b32_e32 v30, s28
	v_mov_b32_e32 v31, s29
	v_mov_b32_e32 v32, s30
	v_mov_b32_e32 v33, s31
	s_lshl_b32 s10, s6, 9
	s_lshl_b32 s11, s6, 12
	s_mov_b64 s[6:7], 0
	s_movk_i32 s13, 0x2000
	v_mov_b32_e32 v3, 0
	s_movk_i32 s14, 0x7fff
	s_mov_b32 s15, 0xffff0000
	s_mov_b32 s16, 0x2700000
	v_mov_b64_e32 v[4:5], s[18:19]
	s_movk_i32 s17, 0x900
	s_mov_b32 s18, 0x10ffff
.LBB0_80:
	v_mul_hi_i32 v2, v1, s12
	v_lshrrev_b32_e32 v7, 31, v2
	v_ashrrev_i32_e32 v2, 17, v2
	v_add_u32_e32 v16, v2, v7
	v_mul_i32_i24_e32 v2, 0x44000, v16
	v_sub_u32_e32 v2, v1, v2
	v_ashrrev_i32_e32 v7, 5, v2
	v_cmp_gt_i32_e32 vcc, s13, v7
	v_ashrrev_i32_e32 v17, 31, v16
	v_ashrrev_i32_e32 v10, 31, v7
	v_cndmask_b32_e32 v8, v32, v30, vcc
	v_cndmask_b32_e32 v9, v33, v31, vcc
	v_add_u32_e32 v2, 0xffffe000, v7
	v_cndmask_b32_e64 v12, 19, 23, vcc
	v_cndmask_b32_e32 v11, 0, v10, vcc
	v_cndmask_b32_e32 v10, v2, v7, vcc
	v_lshlrev_b64 v[12:13], v12, v[16:17]
	v_and_b32_e32 v20, 0xf8, v6
	v_lshlrev_b64 v[10:11], 10, v[10:11]
	v_lshlrev_b32_e32 v2, 2, v20
	v_mad_i64_i32 v[16:17], s[20:21], v16, s16, v[4:5]
	v_add_u32_e32 v1, s10, v1
	v_cmp_lt_i32_e32 vcc, s18, v1
	v_add_u32_e32 v6, s11, v6
	s_or_b64 s[6:7], vcc, s[6:7]
	s_nop 0
	v_lshl_add_u64 v[8:9], v[8:9], 0, v[12:13]
	v_lshl_add_u64 v[8:9], v[8:9], 0, v[10:11]
	v_lshl_add_u64 v[18:19], v[8:9], 0, v[2:3]
	global_load_dwordx4 v[8:11], v[18:19], off
	global_load_dwordx4 v[12:15], v[18:19], off offset:16
	v_mul_lo_u32 v18, v7, s17
	v_ashrrev_i32_e32 v19, 31, v18
	v_lshl_add_u64 v[16:17], v[18:19], 1, v[16:17]
	v_lshlrev_b32_e32 v2, 1, v20
	v_lshl_add_u64 v[16:17], v[16:17], 0, v[2:3]
	s_waitcnt vmcnt(1)
	v_bfe_u32 v2, v8, 16, 1
	v_bfe_u32 v18, v10, 16, 1
	s_waitcnt vmcnt(0)
	v_bfe_u32 v20, v12, 16, 1
	v_bfe_u32 v22, v14, 16, 1
	v_bfe_u32 v7, v9, 16, 1
	v_bfe_u32 v19, v11, 16, 1
	v_bfe_u32 v21, v13, 16, 1
	v_bfe_u32 v23, v15, 16, 1
	v_add3_u32 v2, v8, v2, s14
	v_add3_u32 v8, v10, v18, s14
	v_add3_u32 v10, v12, v20, s14
	v_add3_u32 v12, v14, v22, s14
	v_add3_u32 v7, v9, v7, s14
	v_add3_u32 v9, v11, v19, s14
	v_add3_u32 v11, v13, v21, s14
	v_add3_u32 v13, v15, v23, s14
	v_lshrrev_b32_e32 v2, 16, v2
	v_lshrrev_b32_e32 v14, 16, v8
	v_lshrrev_b32_e32 v10, 16, v10
	v_lshrrev_b32_e32 v12, 16, v12
	v_and_or_b32 v8, v7, s15, v2
	v_and_or_b32 v9, v9, s15, v14
	v_and_or_b32 v10, v11, s15, v10
	v_and_or_b32 v11, v13, s15, v12
	global_store_dwordx4 v[16:17], v[8:11], off
	s_andn2_b64 exec, exec, s[6:7]
	s_cbranch_execnz .LBB0_80
